# rwkv post loop unrolled by two tokens; K prenorm loads batched across tiles
# baseline (speedup 1.0000x reference)
; __device__ __forceinline__ unsigned f2bf(float f) { return pk2(f, f) & 0xffffu; }
; __device__ __forceinline__ void rwkv_post(const Args& c, int l, int gw, int ngw) {
;     ...
;     for (int it0 = gw; it0 < M * 8; it0 += 8 * ngw) {
;         float y[8], vv[8], g[8], bs[8], lw[8], lb[8];
; #pragma unroll
;         for (int q = 0; q < 8; ++q) { const int it = it0 + q * ngw; const int itc = (it < M * 8) ? it : it0;
;             const int h = itc & 7; const size_t tok = (size_t)(itc >> 3); const int ch = h * 64 + i;
;             y[q] = Y[tok * (PW / 2) + ch]; vv[q] = V[tok * 512 + ch]; g[q] = bf2f(MX[tok * 2048 + ch]); bs[q] = rsc_[(tok * 8 + h) * 4 + 2];
;             lw[q] = c.in[16 + z_][l * 512 + ch]; lb[q] = c.in[17 + z_][l * 512 + ch]; }
; #pragma unroll
;         for (int q = 0; q < 8; ++q) { const int it = it0 + q * ngw;
;             const float mean = wave_sum_fast(y[q]) * (1.f / 64.f); const float d = y[q] - mean;
;             const float var = wave_sum_fast(d * d) * (1.f / 64.f);
;             const float yn = d * rsqrtf(var + 64e-5f) * lw[q] + lb[q];
;             if (it < M * 8) { const int h = it & 7; const size_t tok = (size_t)(it >> 3); MX[tok * 2048 + h * 64 + i] = (bf16)f2bf((yn + bs[q] * vv[q]) * g[q]); } }
.Lpost_loop:
	s_cmp_ge_i32 s0, 0x4000
	s_cbranch_scc1 .Lpost_done
	s_add_i32 s22, s0, s1
	s_cmp_ge_i32 s22, 0x4000
	s_cbranch_scc1 .Lpost_single
	s_mul_i32 s2, s0, 0x3800
	s_lshl_b32 s3, s0, 11
	s_lshl_b32 s4, s0, 12
	s_lshl_b32 s5, s0, 7
	v_add_u32_e32 v24, s2, v3
	v_add_u32_e32 v25, s3, v3
	v_add_u32_e32 v26, s4, v4
	v_add_u32_e32 v27, s5, v5
	global_load_dwordx4 v[28:31], v24, s[10:11]
	global_load_dwordx4 v[32:35], v24, s[10:11] offset:16
	global_load_dwordx4 v[36:39], v25, s[12:13]
	global_load_dwordx4 v[40:43], v25, s[12:13] offset:16
	global_load_dwordx4 v[44:47], v26, s[20:21]
	global_load_dword v48, v27, s[6:7]
	s_mul_i32 s2, s22, 0x3800
	s_lshl_b32 s3, s22, 11
	s_lshl_b32 s4, s22, 12
	s_lshl_b32 s5, s22, 7
	v_add_u32_e32 v93, s2, v3
	v_add_u32_e32 v94, s3, v3
	v_add_u32_e32 v95, s4, v4
	v_add_u32_e32 v96, s5, v5
	global_load_dwordx4 v[64:67], v93, s[10:11]
	global_load_dwordx4 v[68:71], v93, s[10:11] offset:16
	global_load_dwordx4 v[76:79], v94, s[12:13]
	global_load_dwordx4 v[80:83], v94, s[12:13] offset:16
	global_load_dwordx4 v[88:91], v95, s[20:21]
	global_load_dword v92, v96, s[6:7]
	s_waitcnt vmcnt(6)
	v_add_f32_e32 v49, v28, v29
	v_add_f32_e32 v50, v30, v31
	v_add_f32_e32 v51, v32, v33
	v_add_f32_e32 v52, v34, v35
	v_add_f32_e32 v49, v49, v50
	v_add_f32_e32 v51, v51, v52
	v_add_f32_e32 v49, v49, v51
	s_nop 1
	v_add_f32_dpp v49, v49, v49 quad_perm:[1,0,3,2] row_mask:0xf bank_mask:0xf bound_ctrl:1
	s_nop 1
	v_add_f32_dpp v49, v49, v49 quad_perm:[2,3,0,1] row_mask:0xf bank_mask:0xf bound_ctrl:1
	s_nop 1
	v_add_f32_dpp v49, v49, v49 row_half_mirror row_mask:0xf bank_mask:0xf bound_ctrl:1
	v_mul_f32_e32 v50, s14, v49
	v_sub_f32_e32 v28, v28, v50
	v_sub_f32_e32 v29, v29, v50
	v_sub_f32_e32 v30, v30, v50
	v_sub_f32_e32 v31, v31, v50
	v_sub_f32_e32 v32, v32, v50
	v_sub_f32_e32 v33, v33, v50
	v_sub_f32_e32 v34, v34, v50
	v_sub_f32_e32 v35, v35, v50
	v_mul_f32_e32 v51, v28, v28
	v_fmac_f32_e32 v51, v29, v29
	v_fmac_f32_e32 v51, v30, v30
	v_fmac_f32_e32 v51, v31, v31
	v_fmac_f32_e32 v51, v32, v32
	v_fmac_f32_e32 v51, v33, v33
	v_fmac_f32_e32 v51, v34, v34
	v_fmac_f32_e32 v51, v35, v35
	s_nop 1
	v_add_f32_dpp v51, v51, v51 quad_perm:[1,0,3,2] row_mask:0xf bank_mask:0xf bound_ctrl:1
	s_nop 1
	v_add_f32_dpp v51, v51, v51 quad_perm:[2,3,0,1] row_mask:0xf bank_mask:0xf bound_ctrl:1
	s_nop 1
	v_add_f32_dpp v51, v51, v51 row_half_mirror row_mask:0xf bank_mask:0xf bound_ctrl:1
	v_fmamk_f32 v52, v51, 0x3c800000, v193
	v_rsq_f32_e32 v53, v52
	s_nop 0
	v_mul_f32_e32 v28, v28, v53
	v_fma_f32 v28, v28, v8, v16
	v_fmac_f32_e32 v28, v48, v36
	v_mul_f32_e32 v29, v29, v53
	v_fma_f32 v29, v29, v9, v17
	v_fmac_f32_e32 v29, v48, v37
	v_mul_f32_e32 v30, v30, v53
	v_fma_f32 v30, v30, v10, v18
	v_fmac_f32_e32 v30, v48, v38
	v_mul_f32_e32 v31, v31, v53
	v_fma_f32 v31, v31, v11, v19
	v_fmac_f32_e32 v31, v48, v39
	v_mul_f32_e32 v32, v32, v53
	v_fma_f32 v32, v32, v12, v20
	v_fmac_f32_e32 v32, v48, v40
	v_mul_f32_e32 v33, v33, v53
	v_fma_f32 v33, v33, v13, v21
	v_fmac_f32_e32 v33, v48, v41
	v_mul_f32_e32 v34, v34, v53
	v_fma_f32 v34, v34, v14, v22
	v_fmac_f32_e32 v34, v48, v42
	v_mul_f32_e32 v35, v35, v53
	v_fma_f32 v35, v35, v15, v23
	v_fmac_f32_e32 v35, v48, v43
	v_lshlrev_b32_e32 v54, 16, v44
	v_and_b32_e32 v55, 0xffff0000, v44
	v_mul_f32_e32 v28, v28, v54
	v_mul_f32_e32 v29, v29, v55
	v_cvt_pk_bf16_f32 v56, v28, v29
	v_lshlrev_b32_e32 v54, 16, v45
	v_and_b32_e32 v55, 0xffff0000, v45
	v_mul_f32_e32 v30, v30, v54
	v_mul_f32_e32 v31, v31, v55
	v_cvt_pk_bf16_f32 v57, v30, v31
	v_lshlrev_b32_e32 v54, 16, v46
	v_and_b32_e32 v55, 0xffff0000, v46
	v_mul_f32_e32 v32, v32, v54
	v_mul_f32_e32 v33, v33, v55
	v_cvt_pk_bf16_f32 v58, v32, v33
	v_lshlrev_b32_e32 v54, 16, v47
	v_and_b32_e32 v55, 0xffff0000, v47
	v_mul_f32_e32 v34, v34, v54
	v_mul_f32_e32 v35, v35, v55
	v_cvt_pk_bf16_f32 v59, v34, v35
	global_store_dwordx4 v26, v[56:59], s[20:21]
	s_waitcnt vmcnt(1)
	v_add_f32_e32 v49, v64, v65
	v_add_f32_e32 v50, v66, v67
	v_add_f32_e32 v51, v68, v69
	v_add_f32_e32 v52, v70, v71
	v_add_f32_e32 v49, v49, v50
	v_add_f32_e32 v51, v51, v52
	v_add_f32_e32 v49, v49, v51
	s_nop 1
	v_add_f32_dpp v49, v49, v49 quad_perm:[1,0,3,2] row_mask:0xf bank_mask:0xf bound_ctrl:1
	s_nop 1
	v_add_f32_dpp v49, v49, v49 quad_perm:[2,3,0,1] row_mask:0xf bank_mask:0xf bound_ctrl:1
	s_nop 1
	v_add_f32_dpp v49, v49, v49 row_half_mirror row_mask:0xf bank_mask:0xf bound_ctrl:1
	v_mul_f32_e32 v50, s14, v49
	v_sub_f32_e32 v64, v64, v50
	v_sub_f32_e32 v65, v65, v50
	v_sub_f32_e32 v66, v66, v50
	v_sub_f32_e32 v67, v67, v50
	v_sub_f32_e32 v68, v68, v50
	v_sub_f32_e32 v69, v69, v50
	v_sub_f32_e32 v70, v70, v50
	v_sub_f32_e32 v71, v71, v50
	v_mul_f32_e32 v51, v64, v64
	v_fmac_f32_e32 v51, v65, v65
	v_fmac_f32_e32 v51, v66, v66
	v_fmac_f32_e32 v51, v67, v67
	v_fmac_f32_e32 v51, v68, v68
	v_fmac_f32_e32 v51, v69, v69
	v_fmac_f32_e32 v51, v70, v70
	v_fmac_f32_e32 v51, v71, v71
	s_nop 1
	v_add_f32_dpp v51, v51, v51 quad_perm:[1,0,3,2] row_mask:0xf bank_mask:0xf bound_ctrl:1
	s_nop 1
	v_add_f32_dpp v51, v51, v51 quad_perm:[2,3,0,1] row_mask:0xf bank_mask:0xf bound_ctrl:1
	s_nop 1
	v_add_f32_dpp v51, v51, v51 row_half_mirror row_mask:0xf bank_mask:0xf bound_ctrl:1
	v_fmamk_f32 v52, v51, 0x3c800000, v193
	v_rsq_f32_e32 v53, v52
	s_nop 0
	v_mul_f32_e32 v64, v64, v53
	v_fma_f32 v64, v64, v8, v16
	v_fmac_f32_e32 v64, v92, v76
	v_mul_f32_e32 v65, v65, v53
	v_fma_f32 v65, v65, v9, v17
	v_fmac_f32_e32 v65, v92, v77
	v_mul_f32_e32 v66, v66, v53
	v_fma_f32 v66, v66, v10, v18
	v_fmac_f32_e32 v66, v92, v78
	v_mul_f32_e32 v67, v67, v53
	v_fma_f32 v67, v67, v11, v19
	v_fmac_f32_e32 v67, v92, v79
	v_mul_f32_e32 v68, v68, v53
	v_fma_f32 v68, v68, v12, v20
	v_fmac_f32_e32 v68, v92, v80
	v_mul_f32_e32 v69, v69, v53
	v_fma_f32 v69, v69, v13, v21
	v_fmac_f32_e32 v69, v92, v81
	v_mul_f32_e32 v70, v70, v53
	v_fma_f32 v70, v70, v14, v22
	v_fmac_f32_e32 v70, v92, v82
	v_mul_f32_e32 v71, v71, v53
	v_fma_f32 v71, v71, v15, v23
	v_fmac_f32_e32 v71, v92, v83
	v_lshlrev_b32_e32 v54, 16, v88
	v_and_b32_e32 v55, 0xffff0000, v88
	v_mul_f32_e32 v64, v64, v54
	v_mul_f32_e32 v65, v65, v55
	v_cvt_pk_bf16_f32 v98, v64, v65
	v_lshlrev_b32_e32 v54, 16, v89
	v_and_b32_e32 v55, 0xffff0000, v89
	v_mul_f32_e32 v66, v66, v54
	v_mul_f32_e32 v67, v67, v55
	v_cvt_pk_bf16_f32 v99, v66, v67
	v_lshlrev_b32_e32 v54, 16, v90
	v_and_b32_e32 v55, 0xffff0000, v90
	v_mul_f32_e32 v68, v68, v54
	v_mul_f32_e32 v69, v69, v55
	v_cvt_pk_bf16_f32 v100, v68, v69
	v_lshlrev_b32_e32 v54, 16, v91
	v_and_b32_e32 v55, 0xffff0000, v91
	v_mul_f32_e32 v70, v70, v54
	v_mul_f32_e32 v71, v71, v55
	v_cvt_pk_bf16_f32 v101, v70, v71
	global_store_dwordx4 v95, v[98:101], s[20:21]
	s_add_i32 s0, s22, s1
	s_branch .Lpost_loop
; __device__ __forceinline__ unsigned f2bf(float f) { return pk2(f, f) & 0xffffu; }
; __device__ __forceinline__ void rwkv_post(const Args& c, int l, int gw, int ngw) {
;     ...
;     for (int it0 = gw; it0 < M * 8; it0 += 8 * ngw) {
;         float y[8], vv[8], g[8], bs[8], lw[8], lb[8];
; #pragma unroll
;         for (int q = 0; q < 8; ++q) { const int it = it0 + q * ngw; const int itc = (it < M * 8) ? it : it0;
;             const int h = itc & 7; const size_t tok = (size_t)(itc >> 3); const int ch = h * 64 + i;
;             y[q] = Y[tok * (PW / 2) + ch]; vv[q] = V[tok * 512 + ch]; g[q] = bf2f(MX[tok * 2048 + ch]); bs[q] = rsc_[(tok * 8 + h) * 4 + 2];
;             lw[q] = c.in[16 + z_][l * 512 + ch]; lb[q] = c.in[17 + z_][l * 512 + ch]; }
; #pragma unroll
;         for (int q = 0; q < 8; ++q) { const int it = it0 + q * ngw;
;             const float mean = wave_sum_fast(y[q]) * (1.f / 64.f); const float d = y[q] - mean;
;             const float var = wave_sum_fast(d * d) * (1.f / 64.f);
;             const float yn = d * rsqrtf(var + 64e-5f) * lw[q] + lb[q];
;             if (it < M * 8) { const int h = it & 7; const size_t tok = (size_t)(it >> 3); MX[tok * 2048 + h * 64 + i] = (bf16)f2bf((yn + bs[q] * vv[q]) * g[q]); } }
.Lpost_single:
	s_mul_i32 s2, s0, 0x3800
	s_lshl_b32 s3, s0, 11
	s_lshl_b32 s4, s0, 12
	s_lshl_b32 s5, s0, 7
	v_add_u32_e32 v24, s2, v3
	v_add_u32_e32 v25, s3, v3
	v_add_u32_e32 v26, s4, v4
	v_add_u32_e32 v27, s5, v5
	global_load_dwordx4 v[28:31], v24, s[10:11]
	global_load_dwordx4 v[32:35], v24, s[10:11] offset:16
	global_load_dwordx4 v[36:39], v25, s[12:13]
	global_load_dwordx4 v[40:43], v25, s[12:13] offset:16
	global_load_dwordx4 v[44:47], v26, s[20:21]
	global_load_dword v48, v27, s[6:7]
	s_waitcnt vmcnt(0)
	v_add_f32_e32 v49, v28, v29
	v_add_f32_e32 v50, v30, v31
	v_add_f32_e32 v51, v32, v33
	v_add_f32_e32 v52, v34, v35
	v_add_f32_e32 v49, v49, v50
	v_add_f32_e32 v51, v51, v52
	v_add_f32_e32 v49, v49, v51
	s_nop 1
	v_add_f32_dpp v49, v49, v49 quad_perm:[1,0,3,2] row_mask:0xf bank_mask:0xf bound_ctrl:1
	s_nop 1
	v_add_f32_dpp v49, v49, v49 quad_perm:[2,3,0,1] row_mask:0xf bank_mask:0xf bound_ctrl:1
	s_nop 1
	v_add_f32_dpp v49, v49, v49 row_half_mirror row_mask:0xf bank_mask:0xf bound_ctrl:1
	v_mul_f32_e32 v50, s14, v49
	v_sub_f32_e32 v28, v28, v50
	v_sub_f32_e32 v29, v29, v50
	v_sub_f32_e32 v30, v30, v50
	v_sub_f32_e32 v31, v31, v50
	v_sub_f32_e32 v32, v32, v50
	v_sub_f32_e32 v33, v33, v50
	v_sub_f32_e32 v34, v34, v50
	v_sub_f32_e32 v35, v35, v50
	v_mul_f32_e32 v51, v28, v28
	v_fmac_f32_e32 v51, v29, v29
	v_fmac_f32_e32 v51, v30, v30
	v_fmac_f32_e32 v51, v31, v31
	v_fmac_f32_e32 v51, v32, v32
	v_fmac_f32_e32 v51, v33, v33
	v_fmac_f32_e32 v51, v34, v34
	v_fmac_f32_e32 v51, v35, v35
	s_nop 1
	v_add_f32_dpp v51, v51, v51 quad_perm:[1,0,3,2] row_mask:0xf bank_mask:0xf bound_ctrl:1
	s_nop 1
	v_add_f32_dpp v51, v51, v51 quad_perm:[2,3,0,1] row_mask:0xf bank_mask:0xf bound_ctrl:1
	s_nop 1
	v_add_f32_dpp v51, v51, v51 row_half_mirror row_mask:0xf bank_mask:0xf bound_ctrl:1
	v_fmamk_f32 v52, v51, 0x3c800000, v193
	v_rsq_f32_e32 v53, v52
	s_nop 0
	v_mul_f32_e32 v28, v28, v53
	v_fma_f32 v28, v28, v8, v16
	v_fmac_f32_e32 v28, v48, v36
	v_mul_f32_e32 v29, v29, v53
	v_fma_f32 v29, v29, v9, v17
	v_fmac_f32_e32 v29, v48, v37
	v_mul_f32_e32 v30, v30, v53
	v_fma_f32 v30, v30, v10, v18
	v_fmac_f32_e32 v30, v48, v38
	v_mul_f32_e32 v31, v31, v53
	v_fma_f32 v31, v31, v11, v19
	v_fmac_f32_e32 v31, v48, v39
	v_mul_f32_e32 v32, v32, v53
	v_fma_f32 v32, v32, v12, v20
	v_fmac_f32_e32 v32, v48, v40
	v_mul_f32_e32 v33, v33, v53
	v_fma_f32 v33, v33, v13, v21
	v_fmac_f32_e32 v33, v48, v41
	v_mul_f32_e32 v34, v34, v53
	v_fma_f32 v34, v34, v14, v22
	v_fmac_f32_e32 v34, v48, v42
	v_mul_f32_e32 v35, v35, v53
	v_fma_f32 v35, v35, v15, v23
	v_fmac_f32_e32 v35, v48, v43
	v_lshlrev_b32_e32 v54, 16, v44
	v_and_b32_e32 v55, 0xffff0000, v44
	v_mul_f32_e32 v28, v28, v54
	v_mul_f32_e32 v29, v29, v55
	v_cvt_pk_bf16_f32 v56, v28, v29
	v_lshlrev_b32_e32 v54, 16, v45
	v_and_b32_e32 v55, 0xffff0000, v45
	v_mul_f32_e32 v30, v30, v54
	v_mul_f32_e32 v31, v31, v55
	v_cvt_pk_bf16_f32 v57, v30, v31
	v_lshlrev_b32_e32 v54, 16, v46
	v_and_b32_e32 v55, 0xffff0000, v46
	v_mul_f32_e32 v32, v32, v54
	v_mul_f32_e32 v33, v33, v55
	v_cvt_pk_bf16_f32 v58, v32, v33
	v_lshlrev_b32_e32 v54, 16, v47
	v_and_b32_e32 v55, 0xffff0000, v47
	v_mul_f32_e32 v34, v34, v54
	v_mul_f32_e32 v35, v35, v55
	v_cvt_pk_bf16_f32 v59, v34, v35
	global_store_dwordx4 v26, v[56:59], s[20:21]
	s_add_i32 s0, s0, s1
	s_branch .Lpost_loop

; #define LAS __attribute__((address_space(3)))
; __device__ __forceinline__ unsigned pk2(float lo, float hi) { f32x2_t v = {lo, hi}; bf16x2_t b = __builtin_convertvector(v, bf16x2_t); return __builtin_bit_cast(unsigned, b); }
; __device__ __forceinline__ void unpack8(u32x4v w, float* f) { f[0] = bflo(w.x); f[1] = bfhi(w.x); f[2] = bflo(w.y); f[3] = bfhi(w.y); f[4] = bflo(w.z); f[5] = bfhi(w.z); f[6] = bflo(w.w); f[7] = bfhi(w.w); }
; __device__ __forceinline__ void attn_unit(const Args& c, int l, int b, int h, int qb, float lam, float lam_init, LAS unsigned char* lds) {
;     ...
;             float f[16]; unpack8(gk0[hh], f); unpack8(gk1[hh], f + 8);
;             float kw[16];
; #pragma unroll
;             for (int e4 = 0; e4 < 4; ++e4) { const f32x4 t4 = ((const f32x4*)kwp)[e4]; kw[4 * e4] = t4.x; kw[4 * e4 + 1] = t4.y; kw[4 * e4 + 2] = t4.z; kw[4 * e4 + 3] = t4.w; }
;             float ss = 0.f;
; #pragma unroll
;             for (int e = 0; e < 16; ++e) ss += f[e] * f[e];
;             ss += __shfl_xor(ss, 1); ss += __shfl_xor(ss, 2);
;             const float sc = rsqrtf(ss * (1.f / 64.f) + 1e-6f);
;             u32x4v o;
;             o.x = pk2(f[0] * sc * kw[0], f[1] * sc * kw[1]); o.y = pk2(f[2] * sc * kw[2], f[3] * sc * kw[3]); o.z = pk2(f[4] * sc * kw[4], f[5] * sc * kw[5]); o.w = pk2(f[6] * sc * kw[6], f[7] * sc * kw[7]);
;             *(LAS u32x4v*)(Kt + kr * 136 + part * 16) = o;
;             o.x = pk2(f[8] * sc * kw[8], f[9] * sc * kw[9]); o.y = pk2(f[10] * sc * kw[10], f[11] * sc * kw[11]); o.z = pk2(f[12] * sc * kw[12], f[13] * sc * kw[13]); o.w = pk2(f[14] * sc * kw[14], f[15] * sc * kw[15]);
;             *(LAS u32x4v*)(Kt + kr * 136 + part * 16 + 8) = o;
.Lkn_loop:
	s_mov_b32 s21, s20
	s_cmpk_lt_i32 s21, 0x400
	s_cbranch_scc0 .Lkn_ld_done
	s_and_b32 s0, s21, 15
	s_lshr_b32 s1, s21, 4
	s_and_b32 s1, s1, 7
	s_lshr_b32 s2, s21, 7
	s_lshl_b32 s2, s2, 11
	s_lshl_b32 s0, s0, 7
	s_or_b32 s0, s0, s2
	s_lshl_b32 s1, s1, 8
	s_addk_i32 s1, 0x2700
	v_add_u32_e32 v2, s0, v6
	v_mul_u32_u24_e32 v2, 0x3800, v2
	v_lshl_add_u32 v2, v5, 5, v2
	v_add_u32_e32 v2, s1, v2
	v_add_u32_e32 v3, 0xe0000, v2
	global_load_dwordx4 v[8:11], v2, s[24:25]
	global_load_dwordx4 v[12:15], v2, s[24:25] offset:16
	global_load_dwordx4 v[16:19], v3, s[24:25]
	global_load_dwordx4 v[20:23], v3, s[24:25] offset:16
	s_mul_i32 s21, s58, 1
	s_add_i32 s21, s20, s21
	s_cmpk_lt_i32 s21, 0x400
	s_cbranch_scc0 .Lkn_ld_done
	s_and_b32 s0, s21, 15
	s_lshr_b32 s1, s21, 4
	s_and_b32 s1, s1, 7
	s_lshr_b32 s2, s21, 7
	s_lshl_b32 s2, s2, 11
	s_lshl_b32 s0, s0, 7
	s_or_b32 s0, s0, s2
	s_lshl_b32 s1, s1, 8
	s_addk_i32 s1, 0x2700
	v_add_u32_e32 v40, s0, v6
	v_mul_u32_u24_e32 v40, 0x3800, v40
	v_lshl_add_u32 v40, v5, 5, v40
	v_add_u32_e32 v40, s1, v40
	v_add_u32_e32 v41, 0xe0000, v40
	global_load_dwordx4 v[76:79], v40, s[24:25]
	global_load_dwordx4 v[80:83], v40, s[24:25] offset:16
	global_load_dwordx4 v[84:87], v41, s[24:25]
	global_load_dwordx4 v[88:91], v41, s[24:25] offset:16
	s_mul_i32 s21, s58, 2
	s_add_i32 s21, s20, s21
	s_cmpk_lt_i32 s21, 0x400
	s_cbranch_scc0 .Lkn_ld_done
	s_and_b32 s0, s21, 15
	s_lshr_b32 s1, s21, 4
	s_and_b32 s1, s1, 7
	s_lshr_b32 s2, s21, 7
	s_lshl_b32 s2, s2, 11
	s_lshl_b32 s0, s0, 7
	s_or_b32 s0, s0, s2
	s_lshl_b32 s1, s1, 8
	s_addk_i32 s1, 0x2700
	v_add_u32_e32 v42, s0, v6
	v_mul_u32_u24_e32 v42, 0x3800, v42
	v_lshl_add_u32 v42, v5, 5, v42
	v_add_u32_e32 v42, s1, v42
	v_add_u32_e32 v43, 0xe0000, v42
	global_load_dwordx4 v[92:95], v42, s[24:25]
	global_load_dwordx4 v[96:99], v42, s[24:25] offset:16
	global_load_dwordx4 v[100:103], v43, s[24:25]
	global_load_dwordx4 v[104:107], v43, s[24:25] offset:16
	s_mul_i32 s21, s58, 3
	s_add_i32 s21, s20, s21
	s_cmpk_lt_i32 s21, 0x400
	s_cbranch_scc0 .Lkn_ld_done
	s_and_b32 s0, s21, 15
	s_lshr_b32 s1, s21, 4
	s_and_b32 s1, s1, 7
	s_lshr_b32 s2, s21, 7
	s_lshl_b32 s2, s2, 11
	s_lshl_b32 s0, s0, 7
	s_or_b32 s0, s0, s2
	s_lshl_b32 s1, s1, 8
	s_addk_i32 s1, 0x2700
	v_add_u32_e32 v44, s0, v6
	v_mul_u32_u24_e32 v44, 0x3800, v44
	v_lshl_add_u32 v44, v5, 5, v44
	v_add_u32_e32 v44, s1, v44
	v_add_u32_e32 v45, 0xe0000, v44
	global_load_dwordx4 v[128:131], v44, s[24:25]
	global_load_dwordx4 v[132:135], v44, s[24:25] offset:16
	global_load_dwordx4 v[136:139], v45, s[24:25]
	global_load_dwordx4 v[140:143], v45, s[24:25] offset:16
.Lkn_ld_done:
	s_waitcnt vmcnt(0)
	s_mov_b32 s21, s20
	s_cmpk_lt_i32 s21, 0x400
	s_cbranch_scc0 .Lkn_cp_done
	v_lshlrev_b32_e32 v56, 16, v8
	v_and_b32_e32 v57, 0xffff0000, v8
	v_lshlrev_b32_e32 v58, 16, v9
	v_and_b32_e32 v59, 0xffff0000, v9
	v_lshlrev_b32_e32 v60, 16, v10
	v_and_b32_e32 v61, 0xffff0000, v10
	v_lshlrev_b32_e32 v62, 16, v11
	v_and_b32_e32 v63, 0xffff0000, v11
	v_lshlrev_b32_e32 v64, 16, v12
	v_and_b32_e32 v65, 0xffff0000, v12
	v_lshlrev_b32_e32 v66, 16, v13
	v_and_b32_e32 v67, 0xffff0000, v13
	v_lshlrev_b32_e32 v68, 16, v14
	v_and_b32_e32 v69, 0xffff0000, v14
	v_lshlrev_b32_e32 v70, 16, v15
	v_and_b32_e32 v71, 0xffff0000, v15
	v_mul_f32_e32 v72, v56, v56
	v_fmac_f32_e32 v72, v57, v57
	v_fmac_f32_e32 v72, v58, v58
	v_fmac_f32_e32 v72, v59, v59
	v_fmac_f32_e32 v72, v60, v60
	v_fmac_f32_e32 v72, v61, v61
	v_fmac_f32_e32 v72, v62, v62
	v_fmac_f32_e32 v72, v63, v63
	v_fmac_f32_e32 v72, v64, v64
	v_fmac_f32_e32 v72, v65, v65
	v_fmac_f32_e32 v72, v66, v66
	v_fmac_f32_e32 v72, v67, v67
	v_fmac_f32_e32 v72, v68, v68
	v_fmac_f32_e32 v72, v69, v69
	v_fmac_f32_e32 v72, v70, v70
	v_fmac_f32_e32 v72, v71, v71
	s_nop 1
	v_add_f32_dpp v72, v72, v72 quad_perm:[1,0,3,2] row_mask:0xf bank_mask:0xf bound_ctrl:1
	s_nop 1
	v_add_f32_dpp v72, v72, v72 quad_perm:[2,3,0,1] row_mask:0xf bank_mask:0xf bound_ctrl:1
	v_fmamk_f32 v73, v72, 0x3c800000, v178
	v_rsq_f32_e32 v74, v73
	s_nop 0
	v_mul_f32_e32 v56, v74, v56
	v_mul_f32_e32 v56, v24, v56
	v_mul_f32_e32 v57, v74, v57
	v_mul_f32_e32 v57, v25, v57
	v_cvt_pk_bf16_f32 v8, v56, v57
	v_mul_f32_e32 v58, v74, v58
	v_mul_f32_e32 v58, v26, v58
	v_mul_f32_e32 v59, v74, v59
	v_mul_f32_e32 v59, v27, v59
	v_cvt_pk_bf16_f32 v9, v58, v59
	v_mul_f32_e32 v60, v74, v60
	v_mul_f32_e32 v60, v28, v60
	v_mul_f32_e32 v61, v74, v61
	v_mul_f32_e32 v61, v29, v61
	v_cvt_pk_bf16_f32 v10, v60, v61
	v_mul_f32_e32 v62, v74, v62
	v_mul_f32_e32 v62, v30, v62
	v_mul_f32_e32 v63, v74, v63
	v_mul_f32_e32 v63, v31, v63
	v_cvt_pk_bf16_f32 v11, v62, v63
	v_mul_f32_e32 v64, v74, v64
	v_mul_f32_e32 v64, v32, v64
	v_mul_f32_e32 v65, v74, v65
	v_mul_f32_e32 v65, v33, v65
	v_cvt_pk_bf16_f32 v12, v64, v65
	v_mul_f32_e32 v66, v74, v66
	v_mul_f32_e32 v66, v34, v66
	v_mul_f32_e32 v67, v74, v67
	v_mul_f32_e32 v67, v35, v67
	v_cvt_pk_bf16_f32 v13, v66, v67
	v_mul_f32_e32 v68, v74, v68
	v_mul_f32_e32 v68, v36, v68
	v_mul_f32_e32 v69, v74, v69
	v_mul_f32_e32 v69, v37, v69
	v_cvt_pk_bf16_f32 v14, v68, v69
	v_mul_f32_e32 v70, v74, v70
	v_mul_f32_e32 v70, v38, v70
	v_mul_f32_e32 v71, v74, v71
	v_mul_f32_e32 v71, v39, v71
	v_cvt_pk_bf16_f32 v15, v70, v71
	v_lshlrev_b32_e32 v56, 16, v16
	v_and_b32_e32 v57, 0xffff0000, v16
	v_lshlrev_b32_e32 v58, 16, v17
	v_and_b32_e32 v59, 0xffff0000, v17
	v_lshlrev_b32_e32 v60, 16, v18
	v_and_b32_e32 v61, 0xffff0000, v18
	v_lshlrev_b32_e32 v62, 16, v19
	v_and_b32_e32 v63, 0xffff0000, v19
	v_lshlrev_b32_e32 v64, 16, v20
	v_and_b32_e32 v65, 0xffff0000, v20
	v_lshlrev_b32_e32 v66, 16, v21
	v_and_b32_e32 v67, 0xffff0000, v21
	v_lshlrev_b32_e32 v68, 16, v22
; #define LAS __attribute__((address_space(3)))
; __device__ __forceinline__ unsigned pk2(float lo, float hi) { f32x2_t v = {lo, hi}; bf16x2_t b = __builtin_convertvector(v, bf16x2_t); return __builtin_bit_cast(unsigned, b); }
; __device__ __forceinline__ void unpack8(u32x4v w, float* f) { f[0] = bflo(w.x); f[1] = bfhi(w.x); f[2] = bflo(w.y); f[3] = bfhi(w.y); f[4] = bflo(w.z); f[5] = bfhi(w.z); f[6] = bflo(w.w); f[7] = bfhi(w.w); }
; __device__ __forceinline__ void attn_unit(const Args& c, int l, int b, int h, int qb, float lam, float lam_init, LAS unsigned char* lds) {
;     ...
;             float f[16]; unpack8(gk0[hh], f); unpack8(gk1[hh], f + 8);
;             float kw[16];
; #pragma unroll
;             for (int e4 = 0; e4 < 4; ++e4) { const f32x4 t4 = ((const f32x4*)kwp)[e4]; kw[4 * e4] = t4.x; kw[4 * e4 + 1] = t4.y; kw[4 * e4 + 2] = t4.z; kw[4 * e4 + 3] = t4.w; }
;             float ss = 0.f;
; #pragma unroll
;             for (int e = 0; e < 16; ++e) ss += f[e] * f[e];
;             ss += __shfl_xor(ss, 1); ss += __shfl_xor(ss, 2);
;             const float sc = rsqrtf(ss * (1.f / 64.f) + 1e-6f);
;             u32x4v o;
;             o.x = pk2(f[0] * sc * kw[0], f[1] * sc * kw[1]); o.y = pk2(f[2] * sc * kw[2], f[3] * sc * kw[3]); o.z = pk2(f[4] * sc * kw[4], f[5] * sc * kw[5]); o.w = pk2(f[6] * sc * kw[6], f[7] * sc * kw[7]);
;             *(LAS u32x4v*)(Kt + kr * 136 + part * 16) = o;
;             o.x = pk2(f[8] * sc * kw[8], f[9] * sc * kw[9]); o.y = pk2(f[10] * sc * kw[10], f[11] * sc * kw[11]); o.z = pk2(f[12] * sc * kw[12], f[13] * sc * kw[13]); o.w = pk2(f[14] * sc * kw[14], f[15] * sc * kw[15]);
;             *(LAS u32x4v*)(Kt + kr * 136 + part * 16 + 8) = o;
	v_and_b32_e32 v69, 0xffff0000, v22
	v_lshlrev_b32_e32 v70, 16, v23
	v_and_b32_e32 v71, 0xffff0000, v23
	v_mul_f32_e32 v72, v56, v56
	v_fmac_f32_e32 v72, v57, v57
	v_fmac_f32_e32 v72, v58, v58
	v_fmac_f32_e32 v72, v59, v59
	v_fmac_f32_e32 v72, v60, v60
	v_fmac_f32_e32 v72, v61, v61
	v_fmac_f32_e32 v72, v62, v62
	v_fmac_f32_e32 v72, v63, v63
	v_fmac_f32_e32 v72, v64, v64
	v_fmac_f32_e32 v72, v65, v65
	v_fmac_f32_e32 v72, v66, v66
	v_fmac_f32_e32 v72, v67, v67
	v_fmac_f32_e32 v72, v68, v68
	v_fmac_f32_e32 v72, v69, v69
	v_fmac_f32_e32 v72, v70, v70
	v_fmac_f32_e32 v72, v71, v71
	s_nop 1
	v_add_f32_dpp v72, v72, v72 quad_perm:[1,0,3,2] row_mask:0xf bank_mask:0xf bound_ctrl:1
	s_nop 1
	v_add_f32_dpp v72, v72, v72 quad_perm:[2,3,0,1] row_mask:0xf bank_mask:0xf bound_ctrl:1
	v_fmamk_f32 v73, v72, 0x3c800000, v178
	v_rsq_f32_e32 v74, v73
	s_nop 0
	v_mul_f32_e32 v56, v74, v56
	v_mul_f32_e32 v56, v24, v56
	v_mul_f32_e32 v57, v74, v57
	v_mul_f32_e32 v57, v25, v57
	v_cvt_pk_bf16_f32 v16, v56, v57
	v_mul_f32_e32 v58, v74, v58
	v_mul_f32_e32 v58, v26, v58
	v_mul_f32_e32 v59, v74, v59
	v_mul_f32_e32 v59, v27, v59
	v_cvt_pk_bf16_f32 v17, v58, v59
	v_mul_f32_e32 v60, v74, v60
	v_mul_f32_e32 v60, v28, v60
	v_mul_f32_e32 v61, v74, v61
	v_mul_f32_e32 v61, v29, v61
	v_cvt_pk_bf16_f32 v18, v60, v61
	v_mul_f32_e32 v62, v74, v62
	v_mul_f32_e32 v62, v30, v62
	v_mul_f32_e32 v63, v74, v63
	v_mul_f32_e32 v63, v31, v63
	v_cvt_pk_bf16_f32 v19, v62, v63
	v_mul_f32_e32 v64, v74, v64
	v_mul_f32_e32 v64, v32, v64
	v_mul_f32_e32 v65, v74, v65
	v_mul_f32_e32 v65, v33, v65
	v_cvt_pk_bf16_f32 v20, v64, v65
	v_mul_f32_e32 v66, v74, v66
	v_mul_f32_e32 v66, v34, v66
	v_mul_f32_e32 v67, v74, v67
	v_mul_f32_e32 v67, v35, v67
	v_cvt_pk_bf16_f32 v21, v66, v67
	v_mul_f32_e32 v68, v74, v68
	v_mul_f32_e32 v68, v36, v68
	v_mul_f32_e32 v69, v74, v69
	v_mul_f32_e32 v69, v37, v69
	v_cvt_pk_bf16_f32 v22, v68, v69
	v_mul_f32_e32 v70, v74, v70
	v_mul_f32_e32 v70, v38, v70
	v_mul_f32_e32 v71, v74, v71
	v_mul_f32_e32 v71, v39, v71
	v_cvt_pk_bf16_f32 v23, v70, v71
	global_store_dwordx4 v2, v[8:11], s[24:25]
	global_store_dwordx4 v2, v[12:15], s[24:25] offset:16
	global_store_dwordx4 v3, v[16:19], s[24:25]
	global_store_dwordx4 v3, v[20:23], s[24:25] offset:16
	s_mul_i32 s21, s58, 1
	s_add_i32 s21, s20, s21
	s_cmpk_lt_i32 s21, 0x400
	s_cbranch_scc0 .Lkn_cp_done
	v_lshlrev_b32_e32 v56, 16, v76
	v_and_b32_e32 v57, 0xffff0000, v76
	v_lshlrev_b32_e32 v58, 16, v77
	v_and_b32_e32 v59, 0xffff0000, v77
	v_lshlrev_b32_e32 v60, 16, v78
	v_and_b32_e32 v61, 0xffff0000, v78
	v_lshlrev_b32_e32 v62, 16, v79
	v_and_b32_e32 v63, 0xffff0000, v79
	v_lshlrev_b32_e32 v64, 16, v80
	v_and_b32_e32 v65, 0xffff0000, v80
	v_lshlrev_b32_e32 v66, 16, v81
	v_and_b32_e32 v67, 0xffff0000, v81
	v_lshlrev_b32_e32 v68, 16, v82
	v_and_b32_e32 v69, 0xffff0000, v82
	v_lshlrev_b32_e32 v70, 16, v83
	v_and_b32_e32 v71, 0xffff0000, v83
	v_mul_f32_e32 v72, v56, v56
	v_fmac_f32_e32 v72, v57, v57
	v_fmac_f32_e32 v72, v58, v58
	v_fmac_f32_e32 v72, v59, v59
	v_fmac_f32_e32 v72, v60, v60
	v_fmac_f32_e32 v72, v61, v61
	v_fmac_f32_e32 v72, v62, v62
	v_fmac_f32_e32 v72, v63, v63
	v_fmac_f32_e32 v72, v64, v64
	v_fmac_f32_e32 v72, v65, v65
	v_fmac_f32_e32 v72, v66, v66
	v_fmac_f32_e32 v72, v67, v67
	v_fmac_f32_e32 v72, v68, v68
	v_fmac_f32_e32 v72, v69, v69
	v_fmac_f32_e32 v72, v70, v70
	v_fmac_f32_e32 v72, v71, v71
	s_nop 1
	v_add_f32_dpp v72, v72, v72 quad_perm:[1,0,3,2] row_mask:0xf bank_mask:0xf bound_ctrl:1
	s_nop 1
	v_add_f32_dpp v72, v72, v72 quad_perm:[2,3,0,1] row_mask:0xf bank_mask:0xf bound_ctrl:1
	v_fmamk_f32 v73, v72, 0x3c800000, v178
	v_rsq_f32_e32 v74, v73
	s_nop 0
	v_mul_f32_e32 v56, v74, v56
	v_mul_f32_e32 v56, v24, v56
	v_mul_f32_e32 v57, v74, v57
	v_mul_f32_e32 v57, v25, v57
	v_cvt_pk_bf16_f32 v76, v56, v57
	v_mul_f32_e32 v58, v74, v58
	v_mul_f32_e32 v58, v26, v58
	v_mul_f32_e32 v59, v74, v59
	v_mul_f32_e32 v59, v27, v59
	v_cvt_pk_bf16_f32 v77, v58, v59
	v_mul_f32_e32 v60, v74, v60
	v_mul_f32_e32 v60, v28, v60
	v_mul_f32_e32 v61, v74, v61
	v_mul_f32_e32 v61, v29, v61
	v_cvt_pk_bf16_f32 v78, v60, v61
	v_mul_f32_e32 v62, v74, v62
	v_mul_f32_e32 v62, v30, v62
	v_mul_f32_e32 v63, v74, v63
	v_mul_f32_e32 v63, v31, v63
	v_cvt_pk_bf16_f32 v79, v62, v63
	v_mul_f32_e32 v64, v74, v64
	v_mul_f32_e32 v64, v32, v64
	v_mul_f32_e32 v65, v74, v65
	v_mul_f32_e32 v65, v33, v65
	v_cvt_pk_bf16_f32 v80, v64, v65
	v_mul_f32_e32 v66, v74, v66
	v_mul_f32_e32 v66, v34, v66
	v_mul_f32_e32 v67, v74, v67
	v_mul_f32_e32 v67, v35, v67
	v_cvt_pk_bf16_f32 v81, v66, v67
	v_mul_f32_e32 v68, v74, v68
	v_mul_f32_e32 v68, v36, v68
	v_mul_f32_e32 v69, v74, v69
	v_mul_f32_e32 v69, v37, v69
	v_cvt_pk_bf16_f32 v82, v68, v69
	v_mul_f32_e32 v70, v74, v70
	v_mul_f32_e32 v70, v38, v70
	v_mul_f32_e32 v71, v74, v71
	v_mul_f32_e32 v71, v39, v71
	v_cvt_pk_bf16_f32 v83, v70, v71
	v_lshlrev_b32_e32 v56, 16, v84
	v_and_b32_e32 v57, 0xffff0000, v84
	v_lshlrev_b32_e32 v58, 16, v85
	v_and_b32_e32 v59, 0xffff0000, v85
	v_lshlrev_b32_e32 v60, 16, v86
	v_and_b32_e32 v61, 0xffff0000, v86
	v_lshlrev_b32_e32 v62, 16, v87
	v_and_b32_e32 v63, 0xffff0000, v87
	v_lshlrev_b32_e32 v64, 16, v88
	v_and_b32_e32 v65, 0xffff0000, v88
	v_lshlrev_b32_e32 v66, 16, v89
	v_and_b32_e32 v67, 0xffff0000, v89
	v_lshlrev_b32_e32 v68, 16, v90
	v_and_b32_e32 v69, 0xffff0000, v90
	v_lshlrev_b32_e32 v70, 16, v91
	v_and_b32_e32 v71, 0xffff0000, v91
	v_mul_f32_e32 v72, v56, v56
	v_fmac_f32_e32 v72, v57, v57
	v_fmac_f32_e32 v72, v58, v58
	v_fmac_f32_e32 v72, v59, v59
	v_fmac_f32_e32 v72, v60, v60
	v_fmac_f32_e32 v72, v61, v61
	v_fmac_f32_e32 v72, v62, v62
	v_fmac_f32_e32 v72, v63, v63
	v_fmac_f32_e32 v72, v64, v64
; #define LAS __attribute__((address_space(3)))
; __device__ __forceinline__ unsigned pk2(float lo, float hi) { f32x2_t v = {lo, hi}; bf16x2_t b = __builtin_convertvector(v, bf16x2_t); return __builtin_bit_cast(unsigned, b); }
; __device__ __forceinline__ void unpack8(u32x4v w, float* f) { f[0] = bflo(w.x); f[1] = bfhi(w.x); f[2] = bflo(w.y); f[3] = bfhi(w.y); f[4] = bflo(w.z); f[5] = bfhi(w.z); f[6] = bflo(w.w); f[7] = bfhi(w.w); }
; __device__ __forceinline__ void attn_unit(const Args& c, int l, int b, int h, int qb, float lam, float lam_init, LAS unsigned char* lds) {
;     ...
;             float f[16]; unpack8(gk0[hh], f); unpack8(gk1[hh], f + 8);
;             float kw[16];
; #pragma unroll
;             for (int e4 = 0; e4 < 4; ++e4) { const f32x4 t4 = ((const f32x4*)kwp)[e4]; kw[4 * e4] = t4.x; kw[4 * e4 + 1] = t4.y; kw[4 * e4 + 2] = t4.z; kw[4 * e4 + 3] = t4.w; }
;             float ss = 0.f;
; #pragma unroll
;             for (int e = 0; e < 16; ++e) ss += f[e] * f[e];
;             ss += __shfl_xor(ss, 1); ss += __shfl_xor(ss, 2);
;             const float sc = rsqrtf(ss * (1.f / 64.f) + 1e-6f);
;             u32x4v o;
;             o.x = pk2(f[0] * sc * kw[0], f[1] * sc * kw[1]); o.y = pk2(f[2] * sc * kw[2], f[3] * sc * kw[3]); o.z = pk2(f[4] * sc * kw[4], f[5] * sc * kw[5]); o.w = pk2(f[6] * sc * kw[6], f[7] * sc * kw[7]);
;             *(LAS u32x4v*)(Kt + kr * 136 + part * 16) = o;
;             o.x = pk2(f[8] * sc * kw[8], f[9] * sc * kw[9]); o.y = pk2(f[10] * sc * kw[10], f[11] * sc * kw[11]); o.z = pk2(f[12] * sc * kw[12], f[13] * sc * kw[13]); o.w = pk2(f[14] * sc * kw[14], f[15] * sc * kw[15]);
;             *(LAS u32x4v*)(Kt + kr * 136 + part * 16 + 8) = o;
	v_fmac_f32_e32 v72, v65, v65
	v_fmac_f32_e32 v72, v66, v66
	v_fmac_f32_e32 v72, v67, v67
	v_fmac_f32_e32 v72, v68, v68
	v_fmac_f32_e32 v72, v69, v69
	v_fmac_f32_e32 v72, v70, v70
	v_fmac_f32_e32 v72, v71, v71
	s_nop 1
	v_add_f32_dpp v72, v72, v72 quad_perm:[1,0,3,2] row_mask:0xf bank_mask:0xf bound_ctrl:1
	s_nop 1
	v_add_f32_dpp v72, v72, v72 quad_perm:[2,3,0,1] row_mask:0xf bank_mask:0xf bound_ctrl:1
	v_fmamk_f32 v73, v72, 0x3c800000, v178
	v_rsq_f32_e32 v74, v73
	s_nop 0
	v_mul_f32_e32 v56, v74, v56
	v_mul_f32_e32 v56, v24, v56
	v_mul_f32_e32 v57, v74, v57
	v_mul_f32_e32 v57, v25, v57
	v_cvt_pk_bf16_f32 v84, v56, v57
	v_mul_f32_e32 v58, v74, v58
	v_mul_f32_e32 v58, v26, v58
	v_mul_f32_e32 v59, v74, v59
	v_mul_f32_e32 v59, v27, v59
	v_cvt_pk_bf16_f32 v85, v58, v59
	v_mul_f32_e32 v60, v74, v60
	v_mul_f32_e32 v60, v28, v60
	v_mul_f32_e32 v61, v74, v61
	v_mul_f32_e32 v61, v29, v61
	v_cvt_pk_bf16_f32 v86, v60, v61
	v_mul_f32_e32 v62, v74, v62
	v_mul_f32_e32 v62, v30, v62
	v_mul_f32_e32 v63, v74, v63
	v_mul_f32_e32 v63, v31, v63
	v_cvt_pk_bf16_f32 v87, v62, v63
	v_mul_f32_e32 v64, v74, v64
	v_mul_f32_e32 v64, v32, v64
	v_mul_f32_e32 v65, v74, v65
	v_mul_f32_e32 v65, v33, v65
	v_cvt_pk_bf16_f32 v88, v64, v65
	v_mul_f32_e32 v66, v74, v66
	v_mul_f32_e32 v66, v34, v66
	v_mul_f32_e32 v67, v74, v67
	v_mul_f32_e32 v67, v35, v67
	v_cvt_pk_bf16_f32 v89, v66, v67
	v_mul_f32_e32 v68, v74, v68
	v_mul_f32_e32 v68, v36, v68
	v_mul_f32_e32 v69, v74, v69
	v_mul_f32_e32 v69, v37, v69
	v_cvt_pk_bf16_f32 v90, v68, v69
	v_mul_f32_e32 v70, v74, v70
	v_mul_f32_e32 v70, v38, v70
	v_mul_f32_e32 v71, v74, v71
	v_mul_f32_e32 v71, v39, v71
	v_cvt_pk_bf16_f32 v91, v70, v71
	global_store_dwordx4 v40, v[76:79], s[24:25]
	global_store_dwordx4 v40, v[80:83], s[24:25] offset:16
	global_store_dwordx4 v41, v[84:87], s[24:25]
	global_store_dwordx4 v41, v[88:91], s[24:25] offset:16
	s_mul_i32 s21, s58, 2
	s_add_i32 s21, s20, s21
	s_cmpk_lt_i32 s21, 0x400
	s_cbranch_scc0 .Lkn_cp_done
	v_lshlrev_b32_e32 v56, 16, v92
	v_and_b32_e32 v57, 0xffff0000, v92
	v_lshlrev_b32_e32 v58, 16, v93
	v_and_b32_e32 v59, 0xffff0000, v93
	v_lshlrev_b32_e32 v60, 16, v94
	v_and_b32_e32 v61, 0xffff0000, v94
	v_lshlrev_b32_e32 v62, 16, v95
	v_and_b32_e32 v63, 0xffff0000, v95
	v_lshlrev_b32_e32 v64, 16, v96
	v_and_b32_e32 v65, 0xffff0000, v96
	v_lshlrev_b32_e32 v66, 16, v97
	v_and_b32_e32 v67, 0xffff0000, v97
	v_lshlrev_b32_e32 v68, 16, v98
	v_and_b32_e32 v69, 0xffff0000, v98
	v_lshlrev_b32_e32 v70, 16, v99
	v_and_b32_e32 v71, 0xffff0000, v99
	v_mul_f32_e32 v72, v56, v56
	v_fmac_f32_e32 v72, v57, v57
	v_fmac_f32_e32 v72, v58, v58
	v_fmac_f32_e32 v72, v59, v59
	v_fmac_f32_e32 v72, v60, v60
	v_fmac_f32_e32 v72, v61, v61
	v_fmac_f32_e32 v72, v62, v62
	v_fmac_f32_e32 v72, v63, v63
	v_fmac_f32_e32 v72, v64, v64
	v_fmac_f32_e32 v72, v65, v65
	v_fmac_f32_e32 v72, v66, v66
	v_fmac_f32_e32 v72, v67, v67
	v_fmac_f32_e32 v72, v68, v68
	v_fmac_f32_e32 v72, v69, v69
	v_fmac_f32_e32 v72, v70, v70
	v_fmac_f32_e32 v72, v71, v71
	s_nop 1
	v_add_f32_dpp v72, v72, v72 quad_perm:[1,0,3,2] row_mask:0xf bank_mask:0xf bound_ctrl:1
	s_nop 1
	v_add_f32_dpp v72, v72, v72 quad_perm:[2,3,0,1] row_mask:0xf bank_mask:0xf bound_ctrl:1
	v_fmamk_f32 v73, v72, 0x3c800000, v178
	v_rsq_f32_e32 v74, v73
	s_nop 0
	v_mul_f32_e32 v56, v74, v56
	v_mul_f32_e32 v56, v24, v56
	v_mul_f32_e32 v57, v74, v57
	v_mul_f32_e32 v57, v25, v57
	v_cvt_pk_bf16_f32 v92, v56, v57
	v_mul_f32_e32 v58, v74, v58
	v_mul_f32_e32 v58, v26, v58
	v_mul_f32_e32 v59, v74, v59
	v_mul_f32_e32 v59, v27, v59
	v_cvt_pk_bf16_f32 v93, v58, v59
	v_mul_f32_e32 v60, v74, v60
	v_mul_f32_e32 v60, v28, v60
	v_mul_f32_e32 v61, v74, v61
	v_mul_f32_e32 v61, v29, v61
	v_cvt_pk_bf16_f32 v94, v60, v61
	v_mul_f32_e32 v62, v74, v62
	v_mul_f32_e32 v62, v30, v62
	v_mul_f32_e32 v63, v74, v63
	v_mul_f32_e32 v63, v31, v63
	v_cvt_pk_bf16_f32 v95, v62, v63
	v_mul_f32_e32 v64, v74, v64
	v_mul_f32_e32 v64, v32, v64
	v_mul_f32_e32 v65, v74, v65
	v_mul_f32_e32 v65, v33, v65
	v_cvt_pk_bf16_f32 v96, v64, v65
	v_mul_f32_e32 v66, v74, v66
	v_mul_f32_e32 v66, v34, v66
	v_mul_f32_e32 v67, v74, v67
	v_mul_f32_e32 v67, v35, v67
	v_cvt_pk_bf16_f32 v97, v66, v67
	v_mul_f32_e32 v68, v74, v68
	v_mul_f32_e32 v68, v36, v68
	v_mul_f32_e32 v69, v74, v69
	v_mul_f32_e32 v69, v37, v69
	v_cvt_pk_bf16_f32 v98, v68, v69
	v_mul_f32_e32 v70, v74, v70
	v_mul_f32_e32 v70, v38, v70
	v_mul_f32_e32 v71, v74, v71
	v_mul_f32_e32 v71, v39, v71
	v_cvt_pk_bf16_f32 v99, v70, v71
	v_lshlrev_b32_e32 v56, 16, v100
	v_and_b32_e32 v57, 0xffff0000, v100
	v_lshlrev_b32_e32 v58, 16, v101
	v_and_b32_e32 v59, 0xffff0000, v101
	v_lshlrev_b32_e32 v60, 16, v102
	v_and_b32_e32 v61, 0xffff0000, v102
	v_lshlrev_b32_e32 v62, 16, v103
	v_and_b32_e32 v63, 0xffff0000, v103
	v_lshlrev_b32_e32 v64, 16, v104
	v_and_b32_e32 v65, 0xffff0000, v104
	v_lshlrev_b32_e32 v66, 16, v105
	v_and_b32_e32 v67, 0xffff0000, v105
	v_lshlrev_b32_e32 v68, 16, v106
	v_and_b32_e32 v69, 0xffff0000, v106
	v_lshlrev_b32_e32 v70, 16, v107
	v_and_b32_e32 v71, 0xffff0000, v107
	v_mul_f32_e32 v72, v56, v56
	v_fmac_f32_e32 v72, v57, v57
	v_fmac_f32_e32 v72, v58, v58
	v_fmac_f32_e32 v72, v59, v59
	v_fmac_f32_e32 v72, v60, v60
	v_fmac_f32_e32 v72, v61, v61
	v_fmac_f32_e32 v72, v62, v62
	v_fmac_f32_e32 v72, v63, v63
	v_fmac_f32_e32 v72, v64, v64
	v_fmac_f32_e32 v72, v65, v65
	v_fmac_f32_e32 v72, v66, v66
	v_fmac_f32_e32 v72, v67, v67
	v_fmac_f32_e32 v72, v68, v68
	v_fmac_f32_e32 v72, v69, v69
	v_fmac_f32_e32 v72, v70, v70
	v_fmac_f32_e32 v72, v71, v71
	s_nop 1
	v_add_f32_dpp v72, v72, v72 quad_perm:[1,0,3,2] row_mask:0xf bank_mask:0xf bound_ctrl:1
	s_nop 1
; #define LAS __attribute__((address_space(3)))
; __device__ __forceinline__ unsigned pk2(float lo, float hi) { f32x2_t v = {lo, hi}; bf16x2_t b = __builtin_convertvector(v, bf16x2_t); return __builtin_bit_cast(unsigned, b); }
; __device__ __forceinline__ void unpack8(u32x4v w, float* f) { f[0] = bflo(w.x); f[1] = bfhi(w.x); f[2] = bflo(w.y); f[3] = bfhi(w.y); f[4] = bflo(w.z); f[5] = bfhi(w.z); f[6] = bflo(w.w); f[7] = bfhi(w.w); }
; __device__ __forceinline__ void attn_unit(const Args& c, int l, int b, int h, int qb, float lam, float lam_init, LAS unsigned char* lds) {
;     ...
;             float f[16]; unpack8(gk0[hh], f); unpack8(gk1[hh], f + 8);
;             float kw[16];
; #pragma unroll
;             for (int e4 = 0; e4 < 4; ++e4) { const f32x4 t4 = ((const f32x4*)kwp)[e4]; kw[4 * e4] = t4.x; kw[4 * e4 + 1] = t4.y; kw[4 * e4 + 2] = t4.z; kw[4 * e4 + 3] = t4.w; }
;             float ss = 0.f;
; #pragma unroll
;             for (int e = 0; e < 16; ++e) ss += f[e] * f[e];
;             ss += __shfl_xor(ss, 1); ss += __shfl_xor(ss, 2);
;             const float sc = rsqrtf(ss * (1.f / 64.f) + 1e-6f);
;             u32x4v o;
;             o.x = pk2(f[0] * sc * kw[0], f[1] * sc * kw[1]); o.y = pk2(f[2] * sc * kw[2], f[3] * sc * kw[3]); o.z = pk2(f[4] * sc * kw[4], f[5] * sc * kw[5]); o.w = pk2(f[6] * sc * kw[6], f[7] * sc * kw[7]);
;             *(LAS u32x4v*)(Kt + kr * 136 + part * 16) = o;
;             o.x = pk2(f[8] * sc * kw[8], f[9] * sc * kw[9]); o.y = pk2(f[10] * sc * kw[10], f[11] * sc * kw[11]); o.z = pk2(f[12] * sc * kw[12], f[13] * sc * kw[13]); o.w = pk2(f[14] * sc * kw[14], f[15] * sc * kw[15]);
;             *(LAS u32x4v*)(Kt + kr * 136 + part * 16 + 8) = o;
	v_add_f32_dpp v72, v72, v72 quad_perm:[2,3,0,1] row_mask:0xf bank_mask:0xf bound_ctrl:1
	v_fmamk_f32 v73, v72, 0x3c800000, v178
	v_rsq_f32_e32 v74, v73
	s_nop 0
	v_mul_f32_e32 v56, v74, v56
	v_mul_f32_e32 v56, v24, v56
	v_mul_f32_e32 v57, v74, v57
	v_mul_f32_e32 v57, v25, v57
	v_cvt_pk_bf16_f32 v100, v56, v57
	v_mul_f32_e32 v58, v74, v58
	v_mul_f32_e32 v58, v26, v58
	v_mul_f32_e32 v59, v74, v59
	v_mul_f32_e32 v59, v27, v59
	v_cvt_pk_bf16_f32 v101, v58, v59
	v_mul_f32_e32 v60, v74, v60
	v_mul_f32_e32 v60, v28, v60
	v_mul_f32_e32 v61, v74, v61
	v_mul_f32_e32 v61, v29, v61
	v_cvt_pk_bf16_f32 v102, v60, v61
	v_mul_f32_e32 v62, v74, v62
	v_mul_f32_e32 v62, v30, v62
	v_mul_f32_e32 v63, v74, v63
	v_mul_f32_e32 v63, v31, v63
	v_cvt_pk_bf16_f32 v103, v62, v63
	v_mul_f32_e32 v64, v74, v64
	v_mul_f32_e32 v64, v32, v64
	v_mul_f32_e32 v65, v74, v65
	v_mul_f32_e32 v65, v33, v65
	v_cvt_pk_bf16_f32 v104, v64, v65
	v_mul_f32_e32 v66, v74, v66
	v_mul_f32_e32 v66, v34, v66
	v_mul_f32_e32 v67, v74, v67
	v_mul_f32_e32 v67, v35, v67
	v_cvt_pk_bf16_f32 v105, v66, v67
	v_mul_f32_e32 v68, v74, v68
	v_mul_f32_e32 v68, v36, v68
	v_mul_f32_e32 v69, v74, v69
	v_mul_f32_e32 v69, v37, v69
	v_cvt_pk_bf16_f32 v106, v68, v69
	v_mul_f32_e32 v70, v74, v70
	v_mul_f32_e32 v70, v38, v70
	v_mul_f32_e32 v71, v74, v71
	v_mul_f32_e32 v71, v39, v71
	v_cvt_pk_bf16_f32 v107, v70, v71
	global_store_dwordx4 v42, v[92:95], s[24:25]
	global_store_dwordx4 v42, v[96:99], s[24:25] offset:16
	global_store_dwordx4 v43, v[100:103], s[24:25]
	global_store_dwordx4 v43, v[104:107], s[24:25] offset:16
	s_mul_i32 s21, s58, 3
	s_add_i32 s21, s20, s21
	s_cmpk_lt_i32 s21, 0x400
	s_cbranch_scc0 .Lkn_cp_done
	v_lshlrev_b32_e32 v56, 16, v128
	v_and_b32_e32 v57, 0xffff0000, v128
	v_lshlrev_b32_e32 v58, 16, v129
	v_and_b32_e32 v59, 0xffff0000, v129
	v_lshlrev_b32_e32 v60, 16, v130
	v_and_b32_e32 v61, 0xffff0000, v130
	v_lshlrev_b32_e32 v62, 16, v131
	v_and_b32_e32 v63, 0xffff0000, v131
	v_lshlrev_b32_e32 v64, 16, v132
	v_and_b32_e32 v65, 0xffff0000, v132
	v_lshlrev_b32_e32 v66, 16, v133
	v_and_b32_e32 v67, 0xffff0000, v133
	v_lshlrev_b32_e32 v68, 16, v134
	v_and_b32_e32 v69, 0xffff0000, v134
	v_lshlrev_b32_e32 v70, 16, v135
	v_and_b32_e32 v71, 0xffff0000, v135
	v_mul_f32_e32 v72, v56, v56
	v_fmac_f32_e32 v72, v57, v57
	v_fmac_f32_e32 v72, v58, v58
	v_fmac_f32_e32 v72, v59, v59
	v_fmac_f32_e32 v72, v60, v60
	v_fmac_f32_e32 v72, v61, v61
	v_fmac_f32_e32 v72, v62, v62
	v_fmac_f32_e32 v72, v63, v63
	v_fmac_f32_e32 v72, v64, v64
	v_fmac_f32_e32 v72, v65, v65
	v_fmac_f32_e32 v72, v66, v66
	v_fmac_f32_e32 v72, v67, v67
	v_fmac_f32_e32 v72, v68, v68
	v_fmac_f32_e32 v72, v69, v69
	v_fmac_f32_e32 v72, v70, v70
	v_fmac_f32_e32 v72, v71, v71
	s_nop 1
	v_add_f32_dpp v72, v72, v72 quad_perm:[1,0,3,2] row_mask:0xf bank_mask:0xf bound_ctrl:1
	s_nop 1
	v_add_f32_dpp v72, v72, v72 quad_perm:[2,3,0,1] row_mask:0xf bank_mask:0xf bound_ctrl:1
	v_fmamk_f32 v73, v72, 0x3c800000, v178
	v_rsq_f32_e32 v74, v73
	s_nop 0
	v_mul_f32_e32 v56, v74, v56
	v_mul_f32_e32 v56, v24, v56
	v_mul_f32_e32 v57, v74, v57
	v_mul_f32_e32 v57, v25, v57
	v_cvt_pk_bf16_f32 v128, v56, v57
	v_mul_f32_e32 v58, v74, v58
	v_mul_f32_e32 v58, v26, v58
	v_mul_f32_e32 v59, v74, v59
	v_mul_f32_e32 v59, v27, v59
	v_cvt_pk_bf16_f32 v129, v58, v59
	v_mul_f32_e32 v60, v74, v60
	v_mul_f32_e32 v60, v28, v60
	v_mul_f32_e32 v61, v74, v61
	v_mul_f32_e32 v61, v29, v61
	v_cvt_pk_bf16_f32 v130, v60, v61
	v_mul_f32_e32 v62, v74, v62
	v_mul_f32_e32 v62, v30, v62
	v_mul_f32_e32 v63, v74, v63
	v_mul_f32_e32 v63, v31, v63
	v_cvt_pk_bf16_f32 v131, v62, v63
	v_mul_f32_e32 v64, v74, v64
	v_mul_f32_e32 v64, v32, v64
	v_mul_f32_e32 v65, v74, v65
	v_mul_f32_e32 v65, v33, v65
	v_cvt_pk_bf16_f32 v132, v64, v65
	v_mul_f32_e32 v66, v74, v66
	v_mul_f32_e32 v66, v34, v66
	v_mul_f32_e32 v67, v74, v67
	v_mul_f32_e32 v67, v35, v67
	v_cvt_pk_bf16_f32 v133, v66, v67
	v_mul_f32_e32 v68, v74, v68
	v_mul_f32_e32 v68, v36, v68
	v_mul_f32_e32 v69, v74, v69
	v_mul_f32_e32 v69, v37, v69
	v_cvt_pk_bf16_f32 v134, v68, v69
	v_mul_f32_e32 v70, v74, v70
	v_mul_f32_e32 v70, v38, v70
	v_mul_f32_e32 v71, v74, v71
	v_mul_f32_e32 v71, v39, v71
	v_cvt_pk_bf16_f32 v135, v70, v71
	v_lshlrev_b32_e32 v56, 16, v136
	v_and_b32_e32 v57, 0xffff0000, v136
	v_lshlrev_b32_e32 v58, 16, v137
	v_and_b32_e32 v59, 0xffff0000, v137
	v_lshlrev_b32_e32 v60, 16, v138
	v_and_b32_e32 v61, 0xffff0000, v138
	v_lshlrev_b32_e32 v62, 16, v139
	v_and_b32_e32 v63, 0xffff0000, v139
	v_lshlrev_b32_e32 v64, 16, v140
	v_and_b32_e32 v65, 0xffff0000, v140
	v_lshlrev_b32_e32 v66, 16, v141
	v_and_b32_e32 v67, 0xffff0000, v141
	v_lshlrev_b32_e32 v68, 16, v142
	v_and_b32_e32 v69, 0xffff0000, v142
	v_lshlrev_b32_e32 v70, 16, v143
	v_and_b32_e32 v71, 0xffff0000, v143
	v_mul_f32_e32 v72, v56, v56
	v_fmac_f32_e32 v72, v57, v57
	v_fmac_f32_e32 v72, v58, v58
	v_fmac_f32_e32 v72, v59, v59
	v_fmac_f32_e32 v72, v60, v60
	v_fmac_f32_e32 v72, v61, v61
	v_fmac_f32_e32 v72, v62, v62
	v_fmac_f32_e32 v72, v63, v63
	v_fmac_f32_e32 v72, v64, v64
	v_fmac_f32_e32 v72, v65, v65
	v_fmac_f32_e32 v72, v66, v66
	v_fmac_f32_e32 v72, v67, v67
	v_fmac_f32_e32 v72, v68, v68
	v_fmac_f32_e32 v72, v69, v69
	v_fmac_f32_e32 v72, v70, v70
	v_fmac_f32_e32 v72, v71, v71
	s_nop 1
	v_add_f32_dpp v72, v72, v72 quad_perm:[1,0,3,2] row_mask:0xf bank_mask:0xf bound_ctrl:1
	s_nop 1
	v_add_f32_dpp v72, v72, v72 quad_perm:[2,3,0,1] row_mask:0xf bank_mask:0xf bound_ctrl:1
	v_fmamk_f32 v73, v72, 0x3c800000, v178
	v_rsq_f32_e32 v74, v73
	s_nop 0
	v_mul_f32_e32 v56, v74, v56
	v_mul_f32_e32 v56, v24, v56
	v_mul_f32_e32 v57, v74, v57
	v_mul_f32_e32 v57, v25, v57
	v_cvt_pk_bf16_f32 v136, v56, v57
	v_mul_f32_e32 v58, v74, v58
	v_mul_f32_e32 v58, v26, v58
	v_mul_f32_e32 v59, v74, v59
	v_mul_f32_e32 v59, v27, v59
	v_cvt_pk_bf16_f32 v137, v58, v59
	v_mul_f32_e32 v60, v74, v60
	v_mul_f32_e32 v60, v28, v60
	v_mul_f32_e32 v61, v74, v61
	v_mul_f32_e32 v61, v29, v61
	v_cvt_pk_bf16_f32 v138, v60, v61
	v_mul_f32_e32 v62, v74, v62
	v_mul_f32_e32 v62, v30, v62
	v_mul_f32_e32 v63, v74, v63
	v_mul_f32_e32 v63, v31, v63
	v_cvt_pk_bf16_f32 v139, v62, v63
	v_mul_f32_e32 v64, v74, v64
	v_mul_f32_e32 v64, v32, v64
	v_mul_f32_e32 v65, v74, v65
	v_mul_f32_e32 v65, v33, v65
	v_cvt_pk_bf16_f32 v140, v64, v65
	v_mul_f32_e32 v66, v74, v66
	v_mul_f32_e32 v66, v34, v66
	v_mul_f32_e32 v67, v74, v67
	v_mul_f32_e32 v67, v35, v67
	v_cvt_pk_bf16_f32 v141, v66, v67
	v_mul_f32_e32 v68, v74, v68
	v_mul_f32_e32 v68, v36, v68
	v_mul_f32_e32 v69, v74, v69
	v_mul_f32_e32 v69, v37, v69
	v_cvt_pk_bf16_f32 v142, v68, v69
	v_mul_f32_e32 v70, v74, v70
	v_mul_f32_e32 v70, v38, v70
	v_mul_f32_e32 v71, v74, v71
	v_mul_f32_e32 v71, v39, v71
	v_cvt_pk_bf16_f32 v143, v70, v71
	global_store_dwordx4 v44, v[128:131], s[24:25]
	global_store_dwordx4 v44, v[132:135], s[24:25] offset:16
	global_store_dwordx4 v45, v[136:139], s[24:25]
	global_store_dwordx4 v45, v[140:143], s[24:25] offset:16
; __device__ __forceinline__ void gdn_prep_unit(const Args& c, int ug, int l, LAS unsigned char* lds) {
;     ...
;         float x = gcs[lane];
; #pragma unroll
;         for (int o = 1; o < 64; o <<= 1) { const float y = __shfl_up(x, o); if (lane >= o) x += y; }
.Lkn_cp_done:
	s_lshl_b32 s21, s58, 2
	s_add_i32 s20, s20, s21
	s_cmpk_lt_i32 s20, 0x400
	s_cbranch_scc1 .Lkn_loop
	v_add_u32_e32 v0, -1, v195
	v_cmp_lt_i32_e32 vcc, v0, v52
	v_readlane_b32 s8, v253, 21
	v_readlane_b32 s10, v253, 15
	v_cndmask_b32_e32 v0, v0, v195, vcc
	v_lshlrev_b32_e32 v127, 2, v0
	v_add_u32_e32 v0, -2, v195
	v_cmp_lt_i32_e32 vcc, v0, v52
	v_readlane_b32 s12, v253, 11
	v_readlane_b32 s0, v253, 19
	v_cndmask_b32_e32 v0, v0, v195, vcc
	v_lshlrev_b32_e32 v144, 2, v0
	v_add_u32_e32 v0, -4, v195
	v_cmp_lt_i32_e32 vcc, v0, v52
	v_readlane_b32 s16, v253, 9
	v_readlane_b32 s9, v253, 22
	v_cndmask_b32_e32 v0, v0, v195, vcc
	v_lshlrev_b32_e32 v145, 2, v0
	v_add_u32_e32 v0, -8, v195
	v_cmp_lt_i32_e32 vcc, v0, v52
	v_readlane_b32 s11, v253, 16
	v_readlane_b32 s13, v253, 12
	v_cndmask_b32_e32 v0, v0, v195, vcc
	v_lshlrev_b32_e32 v146, 2, v0
	v_add_u32_e32 v0, -16, v195
	v_cmp_lt_i32_e32 vcc, v0, v52
	s_mov_b32 s17, s0
	v_readlane_b32 s1, v253, 20
	v_cndmask_b32_e32 v0, v0, v195, vcc
	v_lshlrev_b32_e32 v147, 2, v0
	v_subrev_u32_e32 v0, 32, v195
	v_cmp_lt_i32_e32 vcc, v0, v52
	s_nop 1
	v_cndmask_b32_e32 v0, v0, v195, vcc
	v_lshlrev_b32_e32 v148, 2, v0
	s_branch .LBB0_624
